# scan hand-shake: filled word read before the W_T reads, counted lgkmcnt at the check (on top of the paced version)
# baseline (speedup 1.0000x reference)
.LBB0_989:
	ds_read_b128 v[66:69], v194 offset:8192
	ds_read_b128 v[34:37], v194
	ds_read_b128 v[38:41], v194 offset:32
	ds_read_b128 v[82:85], v194 offset:8224
	v_cvt_pk_bf16_f32 v214, v18, v19
	v_cvt_pk_bf16_f32 v215, v20, v21
	s_waitcnt lgkmcnt(2)
	v_mfma_f32_32x32x16_bf16 v[50:65], v[66:69], v[34:37], 0
	v_cvt_pk_bf16_f32 v216, v22, v23
	v_cvt_pk_bf16_f32 v217, v24, v25
	v_cvt_pk_bf16_f32 v228, v26, v27
	v_cvt_pk_bf16_f32 v229, v28, v29
	v_cvt_pk_bf16_f32 v230, v30, v31
	v_cvt_pk_bf16_f32 v231, v32, v33
	v_add_u32_e32 v106, 0x5000, v196
	s_waitcnt lgkmcnt(0)
	v_mfma_f32_32x32x16_bf16 v[50:65], v[82:85], v[38:41], v[50:65]
	ds_read_b128 v[86:89], v194 offset:8256
	ds_read_b128 v[34:37], v194 offset:64
	ds_read_b128 v[90:93], v194 offset:8288
	ds_read_b128 v[38:41], v194 offset:96
	s_add_i32 s14, s20, 2
	s_and_b64 s[8:9], s[92:93], exec
	s_cselect_b32 s8, s21, s14
	s_lshl_b32 s8, s8, 5
	s_add_i32 s8, s8, s12
	s_add_i32 s18, s21, 2
	s_waitcnt lgkmcnt(2)
	v_mfma_f32_32x32x16_bf16 v[50:65], v[86:89], v[34:37], v[50:65]
	ds_read_b128 v[34:37], v194 offset:4096
	ds_read_b128 v[70:73], v194 offset:12288
	ds_read_b128 v[74:77], v194 offset:4128
	ds_read_b128 v[94:97], v194 offset:12320
	s_cmp_ge_u32 s18, s11
	s_waitcnt lgkmcnt(4)
	v_mfma_f32_32x32x16_bf16 v[50:65], v[90:93], v[38:41], v[50:65]
	s_waitcnt lgkmcnt(2)
	v_mfma_f32_32x32x16_bf16 v[34:49], v[34:37], v[70:73], 0
	s_nop 9
	v_cndmask_b32_e64 v0, 0, v50, s[0:1]
	v_cndmask_b32_e64 v50, 0, v51, s[2:3]
	v_cndmask_b32_e64 v51, 0, v52, s[34:35]
	v_cndmask_b32_e64 v52, 0, v53, s[36:37]
	v_cndmask_b32_e64 v53, 0, v54, s[38:39]
	v_cndmask_b32_e64 v57, 0, v57, s[44:45]
	v_cvt_pk_bf16_f32 v54, v0, v50
	s_waitcnt lgkmcnt(0)
	v_mfma_f32_32x32x16_bf16 v[34:49], v[74:77], v[94:97], v[34:49]
	ds_read_b128 v[74:77], v194 offset:4160
	ds_read_b128 v[98:101], v194 offset:12352
	ds_read_b128 v[78:81], v194 offset:4192
	ds_read_b128 v[102:105], v194 offset:12384
	v_cndmask_b32_e64 v58, 0, v58, s[46:47]
	v_cndmask_b32_e64 v59, 0, v59, s[48:49]
	v_cndmask_b32_e64 v60, 0, v60, s[50:51]
	v_cndmask_b32_e64 v61, 0, v61, s[52:53]
	v_cndmask_b32_e64 v62, 0, v62, s[54:55]
	v_cndmask_b32_e64 v63, 0, v63, s[56:57]
	s_waitcnt lgkmcnt(2)
	v_mfma_f32_32x32x16_bf16 v[34:49], v[74:77], v[98:101], v[34:49]
	v_cndmask_b32_e64 v64, 0, v64, s[58:59]
	v_cndmask_b32_e64 v0, 0, v65, s[60:61]
	v_cvt_pk_bf16_f32 v58, v58, v59
	v_cvt_pk_bf16_f32 v59, v60, v61
	v_cvt_pk_bf16_f32 v60, v62, v63
	v_cvt_pk_bf16_f32 v61, v64, v0
	s_waitcnt lgkmcnt(0)
	v_mfma_f32_32x32x16_bf16 v[34:49], v[78:81], v[102:105], v[34:49]
	v_mfma_f32_32x32x16_bf16 v[66:81], v[66:69], v[70:73], 0
	s_nop 10
	v_cndmask_b32_e64 v34, v34, 0, s[62:63]
	v_cndmask_b32_e64 v35, 0, v35, s[0:1]
	v_cvt_pk_bf16_f32 v34, v34, v35
	v_cndmask_b32_e64 v42, v42, 0, s[76:77]
	v_cndmask_b32_e64 v43, v43, 0, s[78:79]
	v_cvt_pk_bf16_f32 v42, v42, v43
	v_cndmask_b32_e64 v43, v44, 0, s[80:81]
	v_mfma_f32_32x32x16_bf16 v[66:81], v[82:85], v[94:97], v[66:81]
	v_cndmask_b32_e64 v82, 0, v55, s[40:41]
	v_cndmask_b32_e64 v83, 0, v56, s[42:43]
	v_cvt_pk_bf16_f32 v55, v51, v52
	v_cvt_pk_bf16_f32 v56, v53, v82
	v_cvt_pk_bf16_f32 v57, v83, v57
	ds_read_b64_tr_b16 v[146:147], v157 offset:0x4000
	ds_read_b64_tr_b16 v[148:149], v157 offset:0x4000+1024
	ds_read_b64_tr_b16 v[134:135], v157 offset:0x4000+2048
	ds_read_b64_tr_b16 v[136:137], v157 offset:0x4000+3072
	ds_read_b64_tr_b16 v[126:127], v176 offset:0x1000
	ds_read_b64_tr_b16 v[128:129], v176 offset:0x1000+1024
	ds_read_b64_tr_b16 v[122:123], v176 offset:0x1000+2048
	ds_read_b64_tr_b16 v[124:125], v176 offset:0x1000+3072
	ds_read_b64_tr_b16 v[118:119], v176 offset:0x1000+64
	ds_read_b64_tr_b16 v[120:121], v176 offset:0x1000+64+1024
	ds_read_b64_tr_b16 v[114:115], v176 offset:0x1000+64+2048
	ds_read_b64_tr_b16 v[116:117], v176 offset:0x1000+64+3072
	ds_read_b64_tr_b16 v[50:51], v176 offset:0x2000
	ds_read_b64_tr_b16 v[52:53], v176 offset:0x2000+1024
	ds_read_b64_tr_b16 v[138:139], v176 offset:0x2000+2048
	ds_read_b64_tr_b16 v[140:141], v176 offset:0x2000+3072
	ds_read_b64_tr_b16 v[142:143], v176 offset:0x2000+64
	ds_read_b64_tr_b16 v[144:145], v176 offset:0x2000+64+1024
	ds_read_b64_tr_b16 v[130:131], v176 offset:0x2000+64+2048
	ds_read_b64_tr_b16 v[132:133], v176 offset:0x2000+64+3072
	s_waitcnt lgkmcnt(0)
	ds_read2_b64 v[242:245], v106 offset0:4 offset1:6
	v_mfma_f32_32x32x16_bf16 v[66:81], v[86:89], v[98:101], v[66:81]
	ds_read2_b64 v[98:101], v195 offset0:8 offset1:10
	v_cndmask_b32_e64 v44, v45, 0, s[82:83]
	v_cvt_pk_bf16_f32 v43, v43, v44
	v_cndmask_b32_e64 v44, v46, 0, s[84:85]
	v_mfma_f32_32x32x16_bf16 v[66:81], v[90:93], v[102:105], v[66:81]
	ds_read2_b64 v[102:105], v195 offset0:12 offset1:14
	v_mfma_f32_32x32x16_bf16 v[82:97], v[54:57], v[146:149], 0
	ds_read2_b64 v[54:57], v195 offset1:2
	s_nop 8
	v_cndmask_b32_e64 v0, v66, 0, s[62:63]
	v_cndmask_b32_e64 v62, 0, v67, s[0:1]
	v_cndmask_b32_e64 v63, v68, 0, s[64:65]
	v_cndmask_b32_e64 v64, v69, 0, s[66:67]
	v_cndmask_b32_e64 v65, v70, 0, s[68:69]
	v_cndmask_b32_e64 v66, v71, 0, s[70:71]
	v_mfma_f32_32x32x16_bf16 v[82:97], v[58:61], v[134:137], v[82:97]
	ds_read2_b64 v[58:61], v195 offset0:4 offset1:6
	v_cndmask_b32_e64 v67, v73, 0, s[74:75]
	v_cndmask_b32_e64 v213, v75, 0, s[78:79]
	v_cndmask_b32_e64 v218, v76, 0, s[80:81]
	v_cndmask_b32_e64 v219, v77, 0, s[82:83]
	v_cvt_pk_bf16_f32 v75, v12, v13
	v_cvt_pk_bf16_f32 v76, v14, v15
	s_waitcnt lgkmcnt(1)
	v_mfma_f32_32x32x16_bf16 v[82:97], v[54:57], v[214:217], v[82:97]
	v_cndmask_b32_e64 v57, v72, 0, s[72:73]
	v_cvt_pk_bf16_f32 v54, v0, v62
	v_cvt_pk_bf16_f32 v55, v63, v64
	v_cvt_pk_bf16_f32 v56, v65, v66
	v_cvt_pk_bf16_f32 v57, v57, v67
	v_cndmask_b32_e64 v0, v74, 0, s[76:77]
	v_cvt_pk_bf16_f32 v74, v10, v11
	s_waitcnt lgkmcnt(0)
	v_mfma_f32_32x32x16_bf16 v[82:97], v[58:61], v[228:231], v[82:97]
	v_cvt_pk_bf16_f32 v77, v16, v17
	v_cndmask_b32_e64 v237, v78, 0, s[84:85]
	v_cndmask_b32_e64 v246, v79, 0, s[86:87]
	v_cvt_pk_bf16_f32 v78, v0, v213
	v_cvt_pk_bf16_f32 v79, v218, v219
	v_add_u32_e32 v0, 0x3000, v195
	v_mfma_f32_32x32x16_bf16 v[58:73], v[54:57], v[146:149], 0
	v_cvt_pk_bf16_f32 v54, v2, v3
	v_cvt_pk_bf16_f32 v55, v4, v5
	v_cvt_pk_bf16_f32 v56, v6, v7
	v_cvt_pk_bf16_f32 v57, v8, v9
	s_nop 1
	v_mfma_f32_32x32x16_bf16 v[82:97], v[98:101], v[54:57], v[82:97]
	ds_read2_b64 v[98:101], v106 offset1:2
	v_mfma_f32_32x32x16_bf16 v[82:97], v[102:105], v[74:77], v[82:97]
	s_nop 11
	v_cvt_pk_bf16_f32 v82, v82, v83
	v_cvt_pk_bf16_f32 v83, v84, v85
	v_cvt_pk_bf16_f32 v84, v86, v87
	v_cvt_pk_bf16_f32 v85, v88, v89
	s_waitcnt lgkmcnt(0)
	s_nop 0
	v_mfma_f32_32x32x16_bf16 v[98:113], v[98:101], v[82:85], 0
	v_cndmask_b32_e64 v84, v80, 0, s[88:89]
	v_cndmask_b32_e64 v85, v81, 0, s[90:91]
	v_cvt_pk_bf16_f32 v80, v90, v91
	v_cvt_pk_bf16_f32 v81, v92, v93
	v_cvt_pk_bf16_f32 v82, v94, v95
	v_cvt_pk_bf16_f32 v83, v96, v97
	ds_read2_b64 v[90:93], v0 offset0:4 offset1:6
	s_nop 0
	v_mfma_f32_32x32x16_bf16 v[98:113], v[242:245], v[80:83], v[98:113]
	v_cvt_pk_bf16_f32 v80, v237, v246
	v_cvt_pk_bf16_f32 v81, v84, v85
	ds_read2_b64 v[82:85], v0 offset1:2
	s_nop 0
	v_mfma_f32_32x32x16_bf16 v[58:73], v[78:81], v[134:137], v[58:73]
	s_nop 6
	v_cvt_pk_bf16_f32 v86, v98, v99
	v_cvt_pk_bf16_f32 v87, v100, v101
	v_cvt_pk_bf16_f32 v88, v102, v103
	v_cvt_pk_bf16_f32 v89, v104, v105
	v_cvt_pk_bf16_f32 v78, v106, v107
	v_cvt_pk_bf16_f32 v79, v108, v109
	v_cvt_pk_bf16_f32 v80, v110, v111
	s_waitcnt lgkmcnt(0)
	v_mfma_f32_32x32x16_bf16 v[58:73], v[82:85], v[214:217], v[58:73]
	ds_read2_b64 v[82:85], v0 offset0:8 offset1:10
	v_cvt_pk_bf16_f32 v81, v112, v113
	v_mfma_f32_32x32x16_bf16 v[58:73], v[90:93], v[228:231], v[58:73]
	ds_read2_b64 v[90:93], v0 offset0:12 offset1:14
	v_cndmask_b32_e64 v0, v36, 0, s[64:65]
	v_cndmask_b32_e64 v36, v37, 0, s[66:67]
	v_cndmask_b32_e64 v37, v38, 0, s[68:69]
	v_cndmask_b32_e64 v38, v39, 0, s[70:71]
	v_cndmask_b32_e64 v39, v40, 0, s[72:73]
	v_cndmask_b32_e64 v40, v41, 0, s[74:75]
	s_waitcnt lgkmcnt(1)
	v_mfma_f32_32x32x16_bf16 v[58:73], v[82:85], v[54:57], v[58:73]
	v_cvt_pk_bf16_f32 v35, v0, v36
	v_cvt_pk_bf16_f32 v36, v37, v38
	v_cvt_pk_bf16_f32 v37, v39, v40
	v_cndmask_b32_e64 v0, v47, 0, s[86:87]
	v_cvt_pk_bf16_f32 v44, v44, v0
	v_cndmask_b32_e64 v0, v48, 0, s[88:89]
	v_cndmask_b32_e64 v38, v49, 0, s[90:91]
	s_waitcnt lgkmcnt(0)
	v_mfma_f32_32x32x16_bf16 v[58:73], v[90:93], v[74:77], v[58:73]
	v_cvt_pk_bf16_f32 v45, v0, v38
	v_mfma_f32_32x32x16_bf16 v[58:73], v[34:37], v[86:89], v[58:73]
	v_mfma_f32_32x32x16_bf16 v[58:73], v[42:45], v[78:81], v[58:73]
	v_mfma_f32_32x32x16_bf16 v[18:33], v[126:129], v[86:89], v[18:33]
	s_movk_i32 s4, 0x1000
	v_mov_b32_e32 v252, s8
	v_mad_u64_u32 v[250:251], s[6:7], v252, s4, v[158:159]
	s_nop 0
	v_readfirstlane_b32 s6, v250
	v_readfirstlane_b32 s7, v251
	s_nop 10
	global_store_dword v155, v58, s[6:7]
	global_store_dword v197, v59, s[6:7]
	global_store_dword v198, v60, s[6:7]
	global_store_dword v199, v61, s[6:7]
	global_store_dword v200, v62, s[6:7]
	global_store_dword v201, v63, s[6:7]
	global_store_dword v202, v64, s[6:7]
	global_store_dword v203, v65, s[6:7]
	global_store_dword v204, v66, s[6:7]
	global_store_dword v205, v67, s[6:7]
	global_store_dword v206, v68, s[6:7]
	global_store_dword v207, v69, s[6:7]
	global_store_dword v208, v70, s[6:7]
	global_store_dword v209, v71, s[6:7]
	v_mfma_f32_32x32x16_bf16 v[34:49], v[142:145], v[146:149], 0
	global_store_dword v210, v72, s[6:7]
	v_mfma_f32_32x32x16_bf16 v[50:65], v[50:53], v[146:149], 0
	global_store_dword v211, v73, s[6:7]
	v_mov_b32_e32 v252, 0x20800
	ds_read_b32 v252, v252
	v_add_u32_e32 v144, s22, v160
	s_cselect_b64 s[8:9], -1, 0
	s_and_b64 vcc, exec, s[8:9]
	v_mfma_f32_32x32x16_bf16 v[2:17], v[118:121], v[86:89], v[2:17]
	v_mfma_f32_32x32x16_bf16 v[34:49], v[130:133], v[134:137], v[34:49]
	v_mfma_f32_32x32x16_bf16 v[18:33], v[122:125], v[78:81], v[18:33]
	ds_read_b128 v[130:133], v144 offset:22528
	ds_read_b128 v[126:129], v144 offset:22560
	ds_read_b128 v[122:125], v144 offset:22592
	ds_read_b128 v[108:111], v144 offset:22624
	ds_read_b128 v[100:103], v144 offset:22656
	ds_read_b128 v[96:99], v144 offset:22688
	ds_read_b128 v[104:107], v144 offset:22720
	ds_read_b128 v[92:95], v144 offset:22752
	v_mov_b32_e32 v250, s101
	v_mov_b32_e32 v251, s100
	ds_write_b32 v250, v251
	s_mov_b32 s4, 0
	v_mov_b32_e32 v250, 0x20800
	s_waitcnt lgkmcnt(9)
	v_readfirstlane_b32 s5, v252
	s_cmp_gt_u32 s5, s100
	s_cbranch_scc1 .Lsc_go1
